# mem_attn K/V staging de-serialised: the 8 global loads per thread issued together with counted vmcnt waits instead of load-wait-write x8 (both sites)
# baseline (speedup 1.0000x reference)
.LBB0_1372:
	s_lshl_b32 s13, s12, 6
	s_and_b32 s13, s13, 0xc0
	s_lshl_b32 s66, s13, 1
	v_lshl_add_u64 v[4:5], v[56:57], 0, s[66:67]
	v_lshl_add_u64 v[0:1], v[4:5], 0, v[62:63]
	global_load_dwordx4 v[8:11], v[0:1], off
	s_andn2_b64 vcc, exec, s[8:9]
	v_add_u32_e32 v0, s13, v74
	v_ashrrev_i32_e32 v1, 31, v0
	v_lshlrev_b64 v[0:1], 9, v[0:1]
	v_lshl_add_u64 v[0:1], v[58:59], 0, v[0:1]
	global_load_dwordx4 v[12:15], v[0:1], off
	v_lshl_add_u64 v[0:1], v[4:5], 0, v[64:65]
	global_load_dwordx4 v[16:19], v[0:1], off
	v_add_u32_e32 v0, s13, v75
	v_ashrrev_i32_e32 v1, 31, v0
	v_lshlrev_b64 v[0:1], 9, v[0:1]
	v_lshl_add_u64 v[0:1], v[58:59], 0, v[0:1]
	global_load_dwordx4 v[20:23], v[0:1], off
	v_lshl_add_u64 v[0:1], v[4:5], 0, v[66:67]
	global_load_dwordx4 v[24:27], v[0:1], off
	v_add_u32_e32 v0, s13, v76
	v_ashrrev_i32_e32 v1, 31, v0
	v_lshlrev_b64 v[0:1], 9, v[0:1]
	v_lshl_add_u64 v[0:1], v[58:59], 0, v[0:1]
	global_load_dwordx4 v[28:31], v[0:1], off
	v_lshl_add_u64 v[0:1], v[4:5], 0, v[68:69]
	global_load_dwordx4 v[32:35], v[0:1], off
	v_add_u32_e32 v0, s13, v77
	v_ashrrev_i32_e32 v1, 31, v0
	v_lshlrev_b64 v[0:1], 9, v[0:1]
	v_lshl_add_u64 v[0:1], v[58:59], 0, v[0:1]
	global_load_dwordx4 v[36:39], v[0:1], off
	s_waitcnt vmcnt(7)
	ds_write_b128 v79, v[8:11]
	s_waitcnt vmcnt(6)
	ds_write_b128 v80, v[12:15] offset:32768
	s_waitcnt vmcnt(5)
	ds_write_b128 v81, v[16:19]
	s_waitcnt vmcnt(4)
	ds_write_b128 v82, v[20:23] offset:32768
	s_waitcnt vmcnt(3)
	ds_write_b128 v83, v[24:27]
	s_waitcnt vmcnt(2)
	ds_write_b128 v84, v[28:31] offset:32768
	s_waitcnt vmcnt(1)
	ds_write_b128 v85, v[32:35]
	s_waitcnt vmcnt(0)
	ds_write_b128 v86, v[36:39] offset:32768
	s_waitcnt lgkmcnt(0)
	s_barrier
	s_cbranch_vccnz .LBB0_1371
	v_and_b32_e32 v1, 64, v208
	v_xor_b32_e32 v0, 16, v208
	v_add_u32_e32 v1, 64, v1
	v_cmp_lt_i32_e32 vcc, v0, v1
	s_and_b32 s13, s11, 0xffffff00
	v_add_u32_e32 v70, s13, v78
	v_cndmask_b32_e32 v0, v208, v0, vcc
	v_lshlrev_b32_e32 v97, 2, v0
	v_xor_b32_e32 v0, 32, v208
	v_cmp_lt_i32_e32 vcc, v0, v1
	v_lshl_add_u64 v[72:73], v[60:61], 0, s[66:67]
	s_mov_b32 s13, s10
	v_cndmask_b32_e32 v0, v208, v0, vcc
	v_lshlrev_b32_e32 v98, 2, v0

.LBB0_1767:
	s_lshl_b32 s11, s10, 6
	s_and_b32 s11, s11, 0xc0
	s_lshl_b32 s66, s11, 1
	v_lshl_add_u64 v[4:5], v[56:57], 0, s[66:67]
	v_lshl_add_u64 v[0:1], v[4:5], 0, v[62:63]
	global_load_dwordx4 v[8:11], v[0:1], off
	s_andn2_b64 vcc, exec, s[4:5]
	v_add_u32_e32 v0, s11, v74
	v_ashrrev_i32_e32 v1, 31, v0
	v_lshlrev_b64 v[0:1], 9, v[0:1]
	v_lshl_add_u64 v[0:1], v[58:59], 0, v[0:1]
	global_load_dwordx4 v[12:15], v[0:1], off
	v_lshl_add_u64 v[0:1], v[4:5], 0, v[64:65]
	global_load_dwordx4 v[16:19], v[0:1], off
	v_add_u32_e32 v0, s11, v75
	v_ashrrev_i32_e32 v1, 31, v0
	v_lshlrev_b64 v[0:1], 9, v[0:1]
	v_lshl_add_u64 v[0:1], v[58:59], 0, v[0:1]
	global_load_dwordx4 v[20:23], v[0:1], off
	v_lshl_add_u64 v[0:1], v[4:5], 0, v[66:67]
	global_load_dwordx4 v[24:27], v[0:1], off
	v_add_u32_e32 v0, s11, v76
	v_ashrrev_i32_e32 v1, 31, v0
	v_lshlrev_b64 v[0:1], 9, v[0:1]
	v_lshl_add_u64 v[0:1], v[58:59], 0, v[0:1]
	global_load_dwordx4 v[28:31], v[0:1], off
	v_lshl_add_u64 v[0:1], v[4:5], 0, v[68:69]
	global_load_dwordx4 v[32:35], v[0:1], off
	v_add_u32_e32 v0, s11, v77
	v_ashrrev_i32_e32 v1, 31, v0
	v_lshlrev_b64 v[0:1], 9, v[0:1]
	v_lshl_add_u64 v[0:1], v[58:59], 0, v[0:1]
	global_load_dwordx4 v[36:39], v[0:1], off
	s_waitcnt vmcnt(7)
	ds_write_b128 v79, v[8:11]
	s_waitcnt vmcnt(6)
	ds_write_b128 v80, v[12:15] offset:32768
	s_waitcnt vmcnt(5)
	ds_write_b128 v81, v[16:19]
	s_waitcnt vmcnt(4)
	ds_write_b128 v82, v[20:23] offset:32768
	s_waitcnt vmcnt(3)
	ds_write_b128 v83, v[24:27]
	s_waitcnt vmcnt(2)
	ds_write_b128 v84, v[28:31] offset:32768
	s_waitcnt vmcnt(1)
	ds_write_b128 v85, v[32:35]
	s_waitcnt vmcnt(0)
	ds_write_b128 v86, v[36:39] offset:32768
	s_waitcnt lgkmcnt(0)
	s_barrier
	s_cbranch_vccnz .LBB0_1766
	v_and_b32_e32 v1, 64, v208
	v_xor_b32_e32 v0, 16, v208
	v_add_u32_e32 v1, 64, v1
	v_cmp_lt_i32_e32 vcc, v0, v1
	s_and_b32 s11, s9, 0xffffff00
	v_add_u32_e32 v70, s11, v78
	v_cndmask_b32_e32 v0, v208, v0, vcc
	v_lshlrev_b32_e32 v97, 2, v0
	v_xor_b32_e32 v0, 32, v208
	v_cmp_lt_i32_e32 vcc, v0, v1
	v_lshl_add_u64 v[72:73], v[60:61], 0, s[66:67]
	s_mov_b32 s11, s8
	v_cndmask_b32_e32 v0, v208, v0, vcc
	v_lshlrev_b32_e32 v98, 2, v0
